# MFMA order per MMA segment: accumulator chains grouped by A fragment across both B blocks (one A-fragment pair feeds 8 consecutive MFMAs)
# baseline (speedup 1.0000x reference)
.LBB0_182:
	s_add_u32 s57, s22, 0x100
	s_addc_u32 s59, s23, 0
	s_add_u32 s22, s24, 0x80
	v_mov_b32_e32 v0, 0
	s_addc_u32 s23, s25, 0
	s_mov_b32 s24, 0
	v_mov_b32_e32 v1, v0
	v_mov_b32_e32 v2, v0
	v_mov_b32_e32 v3, v0
	v_mov_b32_e32 v4, v0
	v_mov_b32_e32 v5, v0
	v_mov_b32_e32 v6, v0
	v_mov_b32_e32 v7, v0
	v_mov_b32_e32 v8, v0
	v_mov_b32_e32 v9, v0
	v_mov_b32_e32 v10, v0
	v_mov_b32_e32 v11, v0
	v_mov_b32_e32 v16, v0
	v_mov_b32_e32 v17, v0
	v_mov_b32_e32 v18, v0
	v_mov_b32_e32 v19, v0
	v_mov_b32_e32 v24, v0
	v_mov_b32_e32 v25, v0
	v_mov_b32_e32 v26, v0
	v_mov_b32_e32 v27, v0
	v_mov_b32_e32 v32, v0
	v_mov_b32_e32 v33, v0
	v_mov_b32_e32 v34, v0
	v_mov_b32_e32 v35, v0
	v_mov_b32_e32 v48, v0
	v_mov_b32_e32 v49, v0
	v_mov_b32_e32 v50, v0
	v_mov_b32_e32 v51, v0
	v_mov_b32_e32 v52, v0
	v_mov_b32_e32 v53, v0
	v_mov_b32_e32 v54, v0
	v_mov_b32_e32 v55, v0
	v_mov_b32_e32 v12, v0
	v_mov_b32_e32 v13, v0
	v_mov_b32_e32 v14, v0
	v_mov_b32_e32 v15, v0
	v_mov_b32_e32 v20, v0
	v_mov_b32_e32 v21, v0
	v_mov_b32_e32 v22, v0
	v_mov_b32_e32 v23, v0
	v_mov_b32_e32 v28, v0
	v_mov_b32_e32 v29, v0
	v_mov_b32_e32 v30, v0
	v_mov_b32_e32 v31, v0
	v_mov_b32_e32 v36, v0
	v_mov_b32_e32 v37, v0
	v_mov_b32_e32 v38, v0
	v_mov_b32_e32 v39, v0
	v_mov_b32_e32 v40, v0
	v_mov_b32_e32 v41, v0
	v_mov_b32_e32 v42, v0
	v_mov_b32_e32 v43, v0
	v_mov_b32_e32 v44, v0
	v_mov_b32_e32 v45, v0
	v_mov_b32_e32 v46, v0
	v_mov_b32_e32 v47, v0
	v_mov_b32_e32 v56, v0
	v_mov_b32_e32 v57, v0
	v_mov_b32_e32 v58, v0
	v_mov_b32_e32 v59, v0
	v_mov_b32_e32 v60, v0
	v_mov_b32_e32 v61, v0
	v_mov_b32_e32 v62, v0
	v_mov_b32_e32 v63, v0
	v_mov_b32_e32 v64, v0
	v_mov_b32_e32 v65, v0
	v_mov_b32_e32 v66, v0
	v_mov_b32_e32 v67, v0
	v_mov_b32_e32 v68, v0
	v_mov_b32_e32 v69, v0
	v_mov_b32_e32 v70, v0
	v_mov_b32_e32 v71, v0
	v_mov_b32_e32 v72, v0
	v_mov_b32_e32 v73, v0
	v_mov_b32_e32 v74, v0
	v_mov_b32_e32 v75, v0
	v_mov_b32_e32 v84, v0
	v_mov_b32_e32 v85, v0
	v_mov_b32_e32 v86, v0
	v_mov_b32_e32 v87, v0
	v_mov_b32_e32 v96, v0
	v_mov_b32_e32 v97, v0
	v_mov_b32_e32 v98, v0
	v_mov_b32_e32 v99, v0
	v_mov_b32_e32 v100, v0
	v_mov_b32_e32 v101, v0
	v_mov_b32_e32 v102, v0
	v_mov_b32_e32 v103, v0
	v_mov_b32_e32 v128, v0
	v_mov_b32_e32 v129, v0
	v_mov_b32_e32 v130, v0
	v_mov_b32_e32 v131, v0
	v_mov_b32_e32 v132, v0
	v_mov_b32_e32 v133, v0
	v_mov_b32_e32 v134, v0
	v_mov_b32_e32 v135, v0
	v_mov_b32_e32 v76, v0
	v_mov_b32_e32 v77, v0
	v_mov_b32_e32 v78, v0
	v_mov_b32_e32 v79, v0
	v_mov_b32_e32 v80, v0
	v_mov_b32_e32 v81, v0
	v_mov_b32_e32 v82, v0
	v_mov_b32_e32 v83, v0
	v_mov_b32_e32 v88, v0
	v_mov_b32_e32 v89, v0
	v_mov_b32_e32 v90, v0
	v_mov_b32_e32 v91, v0
	v_mov_b32_e32 v92, v0
	v_mov_b32_e32 v93, v0
	v_mov_b32_e32 v94, v0
	v_mov_b32_e32 v95, v0
	v_mov_b32_e32 v120, v0
	v_mov_b32_e32 v121, v0
	v_mov_b32_e32 v122, v0
	v_mov_b32_e32 v123, v0
	v_mov_b32_e32 v124, v0
	v_mov_b32_e32 v125, v0
	v_mov_b32_e32 v126, v0
	v_mov_b32_e32 v127, v0
	v_mov_b32_e32 v136, v0
	v_mov_b32_e32 v137, v0
	v_mov_b32_e32 v138, v0
	v_mov_b32_e32 v139, v0
	v_mov_b32_e32 v140, v0
	v_mov_b32_e32 v141, v0
	v_mov_b32_e32 v142, v0
	v_mov_b32_e32 v143, v0
	v_readlane_b32 s2, v246, 43
	s_cmp_eq_u32 s2, 0
	s_cbranch_scc1 .LBB0_183
	s_add_i32 s60, s24, 2
	s_add_u32 s2, s22, 0x80
	s_addc_u32 s3, s23, 0
	s_add_i32 s61, 0, 0x10000
	s_cmp_eq_u32 s51, s24
	s_cselect_b32 s25, s1, s3
	s_cselect_b32 s24, s0, s2
	s_cselect_b32 s3, s21, s59
	s_cselect_b32 s2, s20, s57
	s_add_i32 s62, 0, 0x14000
	v_add_u32_e32 v116, s61, v192
	v_add_u32_e32 v156, s62, v192
	ds_read_b128 v[104:107], v116
	ds_read_b128 v[108:111], v116 offset:1024
	ds_read_b128 v[112:115], v116 offset:2048
	ds_read_b128 v[116:119], v116 offset:3072
	ds_read_b128 v[144:147], v156
	ds_read_b128 v[148:151], v156 offset:1024
	ds_read_b128 v[152:155], v156 offset:2048
	ds_read_b128 v[156:159], v156 offset:3072
	v_lshl_add_u64 v[190:191], s[22:23], 0, v[188:189]
	s_add_i32 m0, s31, 0xc000
	ds_read_b128 v[160:163], v194
	ds_read_b128 v[164:167], v194 offset:1024
	ds_read_b128 v[196:199], v194 offset:2048
	ds_read_b128 v[200:203], v194 offset:3072
	ds_read_b128 v[210:213], v194 offset:4096
	ds_read_b128 v[214:217], v194 offset:5120
	ds_read_b128 v[218:221], v194 offset:6144
	ds_read_b128 v[222:225], v194 offset:7168
	global_load_lds_dwordx4 v[190:191], off
	v_lshl_add_u64 v[190:191], s[22:23], 0, v[186:187]
	s_add_i32 m0, s31, 0xe000
	s_nop 0
	global_load_lds_dwordx4 v[190:191], off
	s_waitcnt vmcnt(40)
	s_waitcnt lgkmcnt(0)
	s_barrier
	s_setprio 1
	s_waitcnt lgkmcnt(0)
	v_mfma_f32_16x16x32_bf16 v[140:143], v[104:107], v[160:163], v[140:143]
	v_mfma_f32_16x16x32_bf16 v[140:143], v[108:111], v[164:167], v[140:143]
	v_mfma_f32_16x16x32_bf16 v[136:139], v[112:115], v[160:163], v[136:139]
	v_mfma_f32_16x16x32_bf16 v[136:139], v[116:119], v[164:167], v[136:139]
	v_mfma_f32_16x16x32_bf16 v[132:135], v[144:147], v[160:163], v[132:135]
	v_mfma_f32_16x16x32_bf16 v[132:135], v[148:151], v[164:167], v[132:135]
	v_mfma_f32_16x16x32_bf16 v[128:131], v[152:155], v[160:163], v[128:131]
	v_mfma_f32_16x16x32_bf16 v[128:131], v[156:159], v[164:167], v[128:131]
	v_mfma_f32_16x16x32_bf16 v[124:127], v[104:107], v[196:199], v[124:127]
	v_mfma_f32_16x16x32_bf16 v[124:127], v[108:111], v[200:203], v[124:127]
	v_mfma_f32_16x16x32_bf16 v[120:123], v[112:115], v[196:199], v[120:123]
	v_mfma_f32_16x16x32_bf16 v[120:123], v[116:119], v[200:203], v[120:123]
	v_mfma_f32_16x16x32_bf16 v[100:103], v[144:147], v[196:199], v[100:103]
	v_mfma_f32_16x16x32_bf16 v[100:103], v[148:151], v[200:203], v[100:103]
	v_mfma_f32_16x16x32_bf16 v[96:99], v[152:155], v[196:199], v[96:99]
	v_mfma_f32_16x16x32_bf16 v[96:99], v[156:159], v[200:203], v[96:99]
	v_mfma_f32_16x16x32_bf16 v[92:95], v[104:107], v[210:213], v[92:95]
	v_mfma_f32_16x16x32_bf16 v[92:95], v[108:111], v[214:217], v[92:95]
	v_mfma_f32_16x16x32_bf16 v[88:91], v[112:115], v[210:213], v[88:91]
	v_mfma_f32_16x16x32_bf16 v[88:91], v[116:119], v[214:217], v[88:91]
	v_mfma_f32_16x16x32_bf16 v[84:87], v[144:147], v[210:213], v[84:87]
	v_mfma_f32_16x16x32_bf16 v[84:87], v[148:151], v[214:217], v[84:87]
	v_mfma_f32_16x16x32_bf16 v[72:75], v[152:155], v[210:213], v[72:75]
	v_mfma_f32_16x16x32_bf16 v[72:75], v[156:159], v[214:217], v[72:75]
	v_mfma_f32_16x16x32_bf16 v[80:83], v[104:107], v[218:221], v[80:83]
	v_mfma_f32_16x16x32_bf16 v[80:83], v[108:111], v[222:225], v[80:83]
	v_mfma_f32_16x16x32_bf16 v[76:79], v[112:115], v[218:221], v[76:79]
	v_mfma_f32_16x16x32_bf16 v[76:79], v[116:119], v[222:225], v[76:79]
	v_mfma_f32_16x16x32_bf16 v[68:71], v[144:147], v[218:221], v[68:71]
	v_mfma_f32_16x16x32_bf16 v[68:71], v[148:151], v[222:225], v[68:71]
	v_mfma_f32_16x16x32_bf16 v[64:67], v[152:155], v[218:221], v[64:67]
	v_mfma_f32_16x16x32_bf16 v[64:67], v[156:159], v[222:225], v[64:67]
	s_setprio 0
	s_barrier
	s_add_i32 s61, s61, s30
	v_lshl_add_u64 v[190:191], s[2:3], 0, v[174:175]
	s_mov_b32 m0, s61
	ds_read_b128 v[160:163], v194 offset:16384
	ds_read_b128 v[164:167], v194 offset:17408
	ds_read_b128 v[196:199], v194 offset:18432
	ds_read_b128 v[200:203], v194 offset:19456
	ds_read_b128 v[210:213], v194 offset:20480
	ds_read_b128 v[214:217], v194 offset:21504
	ds_read_b128 v[218:221], v194 offset:22528
	ds_read_b128 v[222:225], v194 offset:23552
	global_load_lds_dwordx4 v[190:191], off
	s_add_i32 m0, s61, 0x2000
	v_lshl_add_u64 v[226:227], s[2:3], 0, v[184:185]
	s_add_u32 s2, s2, s27
	s_addc_u32 s3, s3, 0
	s_add_i32 s61, s62, s30
	global_load_lds_dwordx4 v[226:227], off
	v_lshl_add_u64 v[228:229], s[2:3], 0, v[174:175]
	s_mov_b32 m0, s61
	v_lshl_add_u64 v[230:231], s[2:3], 0, v[184:185]
	global_load_lds_dwordx4 v[228:229], off
	s_add_i32 m0, s61, 0x2000
	v_lshl_add_u64 v[232:233], s[24:25], 0, v[168:169]
	global_load_lds_dwordx4 v[230:231], off
	s_mov_b32 m0, s31
	v_lshl_add_u64 v[234:235], s[24:25], 0, v[170:171]
	global_load_lds_dwordx4 v[232:233], off
	s_mov_b32 m0, s34
	s_nop 0
	global_load_lds_dwordx4 v[234:235], off
	s_waitcnt vmcnt(40)
	s_waitcnt lgkmcnt(0)
	s_barrier
	s_setprio 1
	s_waitcnt lgkmcnt(0)
	v_mfma_f32_16x16x32_bf16 v[60:63], v[104:107], v[160:163], v[60:63]
	v_mfma_f32_16x16x32_bf16 v[60:63], v[108:111], v[164:167], v[60:63]
	v_mfma_f32_16x16x32_bf16 v[56:59], v[112:115], v[160:163], v[56:59]
	v_mfma_f32_16x16x32_bf16 v[56:59], v[116:119], v[164:167], v[56:59]
	v_mfma_f32_16x16x32_bf16 v[52:55], v[144:147], v[160:163], v[52:55]
	v_mfma_f32_16x16x32_bf16 v[52:55], v[148:151], v[164:167], v[52:55]
	v_mfma_f32_16x16x32_bf16 v[48:51], v[152:155], v[160:163], v[48:51]
	v_mfma_f32_16x16x32_bf16 v[48:51], v[156:159], v[164:167], v[48:51]
	v_mfma_f32_16x16x32_bf16 v[44:47], v[104:107], v[196:199], v[44:47]
	v_mfma_f32_16x16x32_bf16 v[44:47], v[108:111], v[200:203], v[44:47]
	v_mfma_f32_16x16x32_bf16 v[40:43], v[112:115], v[196:199], v[40:43]
	v_mfma_f32_16x16x32_bf16 v[40:43], v[116:119], v[200:203], v[40:43]
	v_mfma_f32_16x16x32_bf16 v[32:35], v[144:147], v[196:199], v[32:35]
	v_mfma_f32_16x16x32_bf16 v[32:35], v[148:151], v[200:203], v[32:35]
	v_mfma_f32_16x16x32_bf16 v[24:27], v[152:155], v[196:199], v[24:27]
	v_mfma_f32_16x16x32_bf16 v[24:27], v[156:159], v[200:203], v[24:27]
	v_mfma_f32_16x16x32_bf16 v[36:39], v[104:107], v[210:213], v[36:39]
	v_mfma_f32_16x16x32_bf16 v[36:39], v[108:111], v[214:217], v[36:39]
	v_mfma_f32_16x16x32_bf16 v[28:31], v[112:115], v[210:213], v[28:31]
	v_mfma_f32_16x16x32_bf16 v[28:31], v[116:119], v[214:217], v[28:31]
	v_mfma_f32_16x16x32_bf16 v[16:19], v[144:147], v[210:213], v[16:19]
	v_mfma_f32_16x16x32_bf16 v[16:19], v[148:151], v[214:217], v[16:19]
	v_mfma_f32_16x16x32_bf16 v[8:11], v[152:155], v[210:213], v[8:11]
	v_mfma_f32_16x16x32_bf16 v[8:11], v[156:159], v[214:217], v[8:11]
	v_mfma_f32_16x16x32_bf16 v[20:23], v[104:107], v[218:221], v[20:23]
	v_mfma_f32_16x16x32_bf16 v[20:23], v[108:111], v[222:225], v[20:23]
	v_mfma_f32_16x16x32_bf16 v[12:15], v[112:115], v[218:221], v[12:15]
	v_mfma_f32_16x16x32_bf16 v[12:15], v[116:119], v[222:225], v[12:15]
	v_mfma_f32_16x16x32_bf16 v[4:7], v[144:147], v[218:221], v[4:7]
	v_mfma_f32_16x16x32_bf16 v[4:7], v[148:151], v[222:225], v[4:7]
	v_mfma_f32_16x16x32_bf16 v[0:3], v[152:155], v[218:221], v[0:3]
	v_mfma_f32_16x16x32_bf16 v[0:3], v[156:159], v[222:225], v[0:3]
	s_setprio 0
	s_barrier
	s_add_i32 s61, 0, 0x18000
	s_add_i32 s62, 0, 0x1c000
	v_add_u32_e32 v116, s61, v192
	v_add_u32_e32 v156, s62, v192
	ds_read_b128 v[104:107], v116
	ds_read_b128 v[108:111], v116 offset:1024
	ds_read_b128 v[112:115], v116 offset:2048
	ds_read_b128 v[116:119], v116 offset:3072
	ds_read_b128 v[144:147], v156
	ds_read_b128 v[148:151], v156 offset:1024
	ds_read_b128 v[152:155], v156 offset:2048
	ds_read_b128 v[156:159], v156 offset:3072
	s_add_u32 s2, s24, s78
	s_addc_u32 s3, s25, 0
	s_mov_b32 m0, s35
	v_lshl_add_u64 v[236:237], s[2:3], 0, v[168:169]
	ds_read_b128 v[160:163], v194 offset:32768
	ds_read_b128 v[164:167], v194 offset:33792
	ds_read_b128 v[196:199], v194 offset:34816
	ds_read_b128 v[200:203], v194 offset:35840
	ds_read_b128 v[210:213], v194 offset:36864
	ds_read_b128 v[214:217], v194 offset:37888
	ds_read_b128 v[218:221], v194 offset:38912
	ds_read_b128 v[222:225], v194 offset:39936
	global_load_lds_dwordx4 v[236:237], off
	v_lshl_add_u64 v[236:237], s[2:3], 0, v[170:171]
	s_mov_b32 m0, s36
	s_nop 0
	global_load_lds_dwordx4 v[236:237], off
	s_waitcnt vmcnt(8)
	s_waitcnt lgkmcnt(0)
	s_barrier
	s_setprio 1
	s_waitcnt lgkmcnt(0)
	v_mfma_f32_16x16x32_bf16 v[140:143], v[104:107], v[160:163], v[140:143]
	v_mfma_f32_16x16x32_bf16 v[140:143], v[108:111], v[164:167], v[140:143]
	v_mfma_f32_16x16x32_bf16 v[136:139], v[112:115], v[160:163], v[136:139]
	v_mfma_f32_16x16x32_bf16 v[136:139], v[116:119], v[164:167], v[136:139]
	v_mfma_f32_16x16x32_bf16 v[132:135], v[144:147], v[160:163], v[132:135]
	v_mfma_f32_16x16x32_bf16 v[132:135], v[148:151], v[164:167], v[132:135]
	v_mfma_f32_16x16x32_bf16 v[128:131], v[152:155], v[160:163], v[128:131]
	v_mfma_f32_16x16x32_bf16 v[128:131], v[156:159], v[164:167], v[128:131]
	v_mfma_f32_16x16x32_bf16 v[124:127], v[104:107], v[196:199], v[124:127]
	v_mfma_f32_16x16x32_bf16 v[124:127], v[108:111], v[200:203], v[124:127]
	v_mfma_f32_16x16x32_bf16 v[120:123], v[112:115], v[196:199], v[120:123]
	v_mfma_f32_16x16x32_bf16 v[120:123], v[116:119], v[200:203], v[120:123]
	v_mfma_f32_16x16x32_bf16 v[100:103], v[144:147], v[196:199], v[100:103]
	v_mfma_f32_16x16x32_bf16 v[100:103], v[148:151], v[200:203], v[100:103]
	v_mfma_f32_16x16x32_bf16 v[96:99], v[152:155], v[196:199], v[96:99]
	v_mfma_f32_16x16x32_bf16 v[96:99], v[156:159], v[200:203], v[96:99]
	v_mfma_f32_16x16x32_bf16 v[92:95], v[104:107], v[210:213], v[92:95]
	v_mfma_f32_16x16x32_bf16 v[92:95], v[108:111], v[214:217], v[92:95]
	v_mfma_f32_16x16x32_bf16 v[88:91], v[112:115], v[210:213], v[88:91]
	v_mfma_f32_16x16x32_bf16 v[88:91], v[116:119], v[214:217], v[88:91]
	v_mfma_f32_16x16x32_bf16 v[84:87], v[144:147], v[210:213], v[84:87]
	v_mfma_f32_16x16x32_bf16 v[84:87], v[148:151], v[214:217], v[84:87]
	v_mfma_f32_16x16x32_bf16 v[72:75], v[152:155], v[210:213], v[72:75]
	v_mfma_f32_16x16x32_bf16 v[72:75], v[156:159], v[214:217], v[72:75]
	v_mfma_f32_16x16x32_bf16 v[80:83], v[104:107], v[218:221], v[80:83]
	v_mfma_f32_16x16x32_bf16 v[80:83], v[108:111], v[222:225], v[80:83]
	v_mfma_f32_16x16x32_bf16 v[76:79], v[112:115], v[218:221], v[76:79]
	v_mfma_f32_16x16x32_bf16 v[76:79], v[116:119], v[222:225], v[76:79]
	v_mfma_f32_16x16x32_bf16 v[68:71], v[144:147], v[218:221], v[68:71]
	v_mfma_f32_16x16x32_bf16 v[68:71], v[148:151], v[222:225], v[68:71]
	v_mfma_f32_16x16x32_bf16 v[64:67], v[152:155], v[218:221], v[64:67]
	v_mfma_f32_16x16x32_bf16 v[64:67], v[156:159], v[222:225], v[64:67]
	s_setprio 0
	s_barrier
	s_add_i32 s2, s61, s30
	v_lshl_add_u64 v[190:191], v[190:191], 0, s[82:83]
	s_mov_b32 m0, s2
	ds_read_b128 v[160:163], v194 offset:49152
	ds_read_b128 v[164:167], v194 offset:50176
	ds_read_b128 v[196:199], v194 offset:51200
	ds_read_b128 v[200:203], v194 offset:52224
	ds_read_b128 v[210:213], v194 offset:53248
	ds_read_b128 v[214:217], v194 offset:54272
	ds_read_b128 v[218:221], v194 offset:55296
	ds_read_b128 v[222:225], v194 offset:56320
	global_load_lds_dwordx4 v[190:191], off
	v_lshl_add_u64 v[190:191], v[226:227], 0, s[82:83]
	s_add_i32 m0, s2, 0x2000
	s_add_i32 s2, s62, s30
	global_load_lds_dwordx4 v[190:191], off
	v_lshl_add_u64 v[190:191], v[228:229], 0, s[82:83]
	s_mov_b32 m0, s2
	s_nop 0
	global_load_lds_dwordx4 v[190:191], off
	v_lshl_add_u64 v[190:191], v[230:231], 0, s[82:83]
	s_add_i32 m0, s2, 0x2000
	s_nop 0
	global_load_lds_dwordx4 v[190:191], off
	v_lshl_add_u64 v[190:191], v[232:233], 0, s[82:83]
	s_mov_b32 m0, s47
	s_nop 0
	global_load_lds_dwordx4 v[190:191], off
	v_lshl_add_u64 v[190:191], v[234:235], 0, s[82:83]
	s_mov_b32 m0, s50
	s_nop 0
	global_load_lds_dwordx4 v[190:191], off
	s_waitcnt vmcnt(8)
	s_waitcnt lgkmcnt(0)
	s_barrier
	s_setprio 1
	s_waitcnt lgkmcnt(0)
	v_mfma_f32_16x16x32_bf16 v[60:63], v[104:107], v[160:163], v[60:63]
	v_mfma_f32_16x16x32_bf16 v[60:63], v[108:111], v[164:167], v[60:63]
	v_mfma_f32_16x16x32_bf16 v[56:59], v[112:115], v[160:163], v[56:59]
	v_mfma_f32_16x16x32_bf16 v[56:59], v[116:119], v[164:167], v[56:59]
	v_mfma_f32_16x16x32_bf16 v[52:55], v[144:147], v[160:163], v[52:55]
	v_mfma_f32_16x16x32_bf16 v[52:55], v[148:151], v[164:167], v[52:55]
	v_mfma_f32_16x16x32_bf16 v[48:51], v[152:155], v[160:163], v[48:51]
	v_mfma_f32_16x16x32_bf16 v[48:51], v[156:159], v[164:167], v[48:51]
	v_mfma_f32_16x16x32_bf16 v[44:47], v[104:107], v[196:199], v[44:47]
	v_mfma_f32_16x16x32_bf16 v[44:47], v[108:111], v[200:203], v[44:47]
	v_mfma_f32_16x16x32_bf16 v[40:43], v[112:115], v[196:199], v[40:43]
	v_mfma_f32_16x16x32_bf16 v[40:43], v[116:119], v[200:203], v[40:43]
	v_mfma_f32_16x16x32_bf16 v[32:35], v[144:147], v[196:199], v[32:35]
	v_mfma_f32_16x16x32_bf16 v[32:35], v[148:151], v[200:203], v[32:35]
	v_mfma_f32_16x16x32_bf16 v[24:27], v[152:155], v[196:199], v[24:27]
	v_mfma_f32_16x16x32_bf16 v[24:27], v[156:159], v[200:203], v[24:27]
	v_mfma_f32_16x16x32_bf16 v[36:39], v[104:107], v[210:213], v[36:39]
	v_mfma_f32_16x16x32_bf16 v[36:39], v[108:111], v[214:217], v[36:39]
	v_mfma_f32_16x16x32_bf16 v[28:31], v[112:115], v[210:213], v[28:31]
	v_mfma_f32_16x16x32_bf16 v[28:31], v[116:119], v[214:217], v[28:31]
	v_mfma_f32_16x16x32_bf16 v[16:19], v[144:147], v[210:213], v[16:19]
	v_mfma_f32_16x16x32_bf16 v[16:19], v[148:151], v[214:217], v[16:19]
	v_mfma_f32_16x16x32_bf16 v[8:11], v[152:155], v[210:213], v[8:11]
	v_mfma_f32_16x16x32_bf16 v[8:11], v[156:159], v[214:217], v[8:11]
	v_mfma_f32_16x16x32_bf16 v[20:23], v[104:107], v[218:221], v[20:23]
	v_mfma_f32_16x16x32_bf16 v[20:23], v[108:111], v[222:225], v[20:23]
	v_mfma_f32_16x16x32_bf16 v[12:15], v[112:115], v[218:221], v[12:15]
	v_mfma_f32_16x16x32_bf16 v[12:15], v[116:119], v[222:225], v[12:15]
	v_mfma_f32_16x16x32_bf16 v[4:7], v[144:147], v[218:221], v[4:7]
	v_mfma_f32_16x16x32_bf16 v[4:7], v[148:151], v[222:225], v[4:7]
	v_mfma_f32_16x16x32_bf16 v[0:3], v[152:155], v[218:221], v[0:3]
	v_mfma_f32_16x16x32_bf16 v[0:3], v[156:159], v[222:225], v[0:3]
	s_setprio 0
	s_barrier
	s_add_u32 s57, s57, 0x100
	s_addc_u32 s59, s59, 0
	s_add_u32 s22, s22, 0x100
	s_addc_u32 s23, s23, 0
	s_cmp_ge_u32 s60, s46
	s_mov_b32 s24, s60
	s_cbranch_scc1 .Lexit_183
.LBB0_183:
	s_add_i32 s60, s24, 2
	s_add_u32 s2, s22, 0x80
	s_addc_u32 s3, s23, 0
	s_add_i32 s61, 0, 0x10000
	s_cmp_eq_u32 s51, s24
	s_cselect_b32 s25, s1, s3
	s_cselect_b32 s24, s0, s2
	s_cselect_b32 s3, s21, s59
	s_cselect_b32 s2, s20, s57
	s_add_i32 s62, 0, 0x14000
	v_add_u32_e32 v116, s61, v192
	v_add_u32_e32 v156, s62, v192
	ds_read_b128 v[104:107], v116
	ds_read_b128 v[108:111], v116 offset:1024
	ds_read_b128 v[112:115], v116 offset:2048
	ds_read_b128 v[116:119], v116 offset:3072
	ds_read_b128 v[144:147], v156
	ds_read_b128 v[148:151], v156 offset:1024
	ds_read_b128 v[152:155], v156 offset:2048
	ds_read_b128 v[156:159], v156 offset:3072
	v_lshl_add_u64 v[190:191], s[22:23], 0, v[188:189]
	s_add_i32 m0, s31, 0xc000
	ds_read_b128 v[160:163], v194
	ds_read_b128 v[164:167], v194 offset:1024
	ds_read_b128 v[196:199], v194 offset:2048
	ds_read_b128 v[200:203], v194 offset:3072
	ds_read_b128 v[210:213], v194 offset:4096
	ds_read_b128 v[214:217], v194 offset:5120
	ds_read_b128 v[218:221], v194 offset:6144
	ds_read_b128 v[222:225], v194 offset:7168
	global_load_lds_dwordx4 v[190:191], off
	v_lshl_add_u64 v[190:191], s[22:23], 0, v[186:187]
	s_add_i32 m0, s31, 0xe000
	s_nop 0
	global_load_lds_dwordx4 v[190:191], off
	s_waitcnt vmcnt(8)
	s_waitcnt lgkmcnt(0)
	s_barrier
	s_setprio 1
	s_waitcnt lgkmcnt(0)
	v_mfma_f32_16x16x32_bf16 v[140:143], v[104:107], v[160:163], v[140:143]
	v_mfma_f32_16x16x32_bf16 v[140:143], v[108:111], v[164:167], v[140:143]
	v_mfma_f32_16x16x32_bf16 v[136:139], v[112:115], v[160:163], v[136:139]
	v_mfma_f32_16x16x32_bf16 v[136:139], v[116:119], v[164:167], v[136:139]
	v_mfma_f32_16x16x32_bf16 v[132:135], v[144:147], v[160:163], v[132:135]
	v_mfma_f32_16x16x32_bf16 v[132:135], v[148:151], v[164:167], v[132:135]
	v_mfma_f32_16x16x32_bf16 v[128:131], v[152:155], v[160:163], v[128:131]
	v_mfma_f32_16x16x32_bf16 v[128:131], v[156:159], v[164:167], v[128:131]
	v_mfma_f32_16x16x32_bf16 v[124:127], v[104:107], v[196:199], v[124:127]
	v_mfma_f32_16x16x32_bf16 v[124:127], v[108:111], v[200:203], v[124:127]
	v_mfma_f32_16x16x32_bf16 v[120:123], v[112:115], v[196:199], v[120:123]
	v_mfma_f32_16x16x32_bf16 v[120:123], v[116:119], v[200:203], v[120:123]
	v_mfma_f32_16x16x32_bf16 v[100:103], v[144:147], v[196:199], v[100:103]
	v_mfma_f32_16x16x32_bf16 v[100:103], v[148:151], v[200:203], v[100:103]
	v_mfma_f32_16x16x32_bf16 v[96:99], v[152:155], v[196:199], v[96:99]
	v_mfma_f32_16x16x32_bf16 v[96:99], v[156:159], v[200:203], v[96:99]
	v_mfma_f32_16x16x32_bf16 v[92:95], v[104:107], v[210:213], v[92:95]
	v_mfma_f32_16x16x32_bf16 v[92:95], v[108:111], v[214:217], v[92:95]
	v_mfma_f32_16x16x32_bf16 v[88:91], v[112:115], v[210:213], v[88:91]
	v_mfma_f32_16x16x32_bf16 v[88:91], v[116:119], v[214:217], v[88:91]
	v_mfma_f32_16x16x32_bf16 v[84:87], v[144:147], v[210:213], v[84:87]
	v_mfma_f32_16x16x32_bf16 v[84:87], v[148:151], v[214:217], v[84:87]
	v_mfma_f32_16x16x32_bf16 v[72:75], v[152:155], v[210:213], v[72:75]
	v_mfma_f32_16x16x32_bf16 v[72:75], v[156:159], v[214:217], v[72:75]
	v_mfma_f32_16x16x32_bf16 v[80:83], v[104:107], v[218:221], v[80:83]
	v_mfma_f32_16x16x32_bf16 v[80:83], v[108:111], v[222:225], v[80:83]
	v_mfma_f32_16x16x32_bf16 v[76:79], v[112:115], v[218:221], v[76:79]
	v_mfma_f32_16x16x32_bf16 v[76:79], v[116:119], v[222:225], v[76:79]
	v_mfma_f32_16x16x32_bf16 v[68:71], v[144:147], v[218:221], v[68:71]
	v_mfma_f32_16x16x32_bf16 v[68:71], v[148:151], v[222:225], v[68:71]
	v_mfma_f32_16x16x32_bf16 v[64:67], v[152:155], v[218:221], v[64:67]
	v_mfma_f32_16x16x32_bf16 v[64:67], v[156:159], v[222:225], v[64:67]
	s_setprio 0
	s_barrier
	s_add_i32 s61, s61, s30
	v_lshl_add_u64 v[190:191], s[2:3], 0, v[174:175]
	s_mov_b32 m0, s61
	ds_read_b128 v[160:163], v194 offset:16384
	ds_read_b128 v[164:167], v194 offset:17408
	ds_read_b128 v[196:199], v194 offset:18432
	ds_read_b128 v[200:203], v194 offset:19456
	ds_read_b128 v[210:213], v194 offset:20480
	ds_read_b128 v[214:217], v194 offset:21504
	ds_read_b128 v[218:221], v194 offset:22528
	ds_read_b128 v[222:225], v194 offset:23552
	global_load_lds_dwordx4 v[190:191], off
	s_add_i32 m0, s61, 0x2000
	v_lshl_add_u64 v[226:227], s[2:3], 0, v[184:185]
	s_add_u32 s2, s2, s27
	s_addc_u32 s3, s3, 0
	s_add_i32 s61, s62, s30
	global_load_lds_dwordx4 v[226:227], off
	v_lshl_add_u64 v[228:229], s[2:3], 0, v[174:175]
	s_mov_b32 m0, s61
	v_lshl_add_u64 v[230:231], s[2:3], 0, v[184:185]
	global_load_lds_dwordx4 v[228:229], off
	s_add_i32 m0, s61, 0x2000
	v_lshl_add_u64 v[232:233], s[24:25], 0, v[168:169]
	global_load_lds_dwordx4 v[230:231], off
	s_mov_b32 m0, s31
	v_lshl_add_u64 v[234:235], s[24:25], 0, v[170:171]
	global_load_lds_dwordx4 v[232:233], off
	s_mov_b32 m0, s34
	s_nop 0
	global_load_lds_dwordx4 v[234:235], off
	s_waitcnt vmcnt(8)
	s_waitcnt lgkmcnt(0)
	s_barrier
	s_setprio 1
	s_waitcnt lgkmcnt(0)
	v_mfma_f32_16x16x32_bf16 v[60:63], v[104:107], v[160:163], v[60:63]
	v_mfma_f32_16x16x32_bf16 v[60:63], v[108:111], v[164:167], v[60:63]
	v_mfma_f32_16x16x32_bf16 v[56:59], v[112:115], v[160:163], v[56:59]
	v_mfma_f32_16x16x32_bf16 v[56:59], v[116:119], v[164:167], v[56:59]
	v_mfma_f32_16x16x32_bf16 v[52:55], v[144:147], v[160:163], v[52:55]
	v_mfma_f32_16x16x32_bf16 v[52:55], v[148:151], v[164:167], v[52:55]
	v_mfma_f32_16x16x32_bf16 v[48:51], v[152:155], v[160:163], v[48:51]
	v_mfma_f32_16x16x32_bf16 v[48:51], v[156:159], v[164:167], v[48:51]
	v_mfma_f32_16x16x32_bf16 v[44:47], v[104:107], v[196:199], v[44:47]
	v_mfma_f32_16x16x32_bf16 v[44:47], v[108:111], v[200:203], v[44:47]
	v_mfma_f32_16x16x32_bf16 v[40:43], v[112:115], v[196:199], v[40:43]
	v_mfma_f32_16x16x32_bf16 v[40:43], v[116:119], v[200:203], v[40:43]
	v_mfma_f32_16x16x32_bf16 v[32:35], v[144:147], v[196:199], v[32:35]
	v_mfma_f32_16x16x32_bf16 v[32:35], v[148:151], v[200:203], v[32:35]
	v_mfma_f32_16x16x32_bf16 v[24:27], v[152:155], v[196:199], v[24:27]
	v_mfma_f32_16x16x32_bf16 v[24:27], v[156:159], v[200:203], v[24:27]
	v_mfma_f32_16x16x32_bf16 v[36:39], v[104:107], v[210:213], v[36:39]
	v_mfma_f32_16x16x32_bf16 v[36:39], v[108:111], v[214:217], v[36:39]
	v_mfma_f32_16x16x32_bf16 v[28:31], v[112:115], v[210:213], v[28:31]
	v_mfma_f32_16x16x32_bf16 v[28:31], v[116:119], v[214:217], v[28:31]
	v_mfma_f32_16x16x32_bf16 v[16:19], v[144:147], v[210:213], v[16:19]
	v_mfma_f32_16x16x32_bf16 v[16:19], v[148:151], v[214:217], v[16:19]
	v_mfma_f32_16x16x32_bf16 v[8:11], v[152:155], v[210:213], v[8:11]
	v_mfma_f32_16x16x32_bf16 v[8:11], v[156:159], v[214:217], v[8:11]
	v_mfma_f32_16x16x32_bf16 v[20:23], v[104:107], v[218:221], v[20:23]
	v_mfma_f32_16x16x32_bf16 v[20:23], v[108:111], v[222:225], v[20:23]
	v_mfma_f32_16x16x32_bf16 v[12:15], v[112:115], v[218:221], v[12:15]
	v_mfma_f32_16x16x32_bf16 v[12:15], v[116:119], v[222:225], v[12:15]
	v_mfma_f32_16x16x32_bf16 v[4:7], v[144:147], v[218:221], v[4:7]
	v_mfma_f32_16x16x32_bf16 v[4:7], v[148:151], v[222:225], v[4:7]
	v_mfma_f32_16x16x32_bf16 v[0:3], v[152:155], v[218:221], v[0:3]
	v_mfma_f32_16x16x32_bf16 v[0:3], v[156:159], v[222:225], v[0:3]
	s_setprio 0
	s_barrier
	s_add_i32 s61, 0, 0x18000
	s_add_i32 s62, 0, 0x1c000
	v_add_u32_e32 v116, s61, v192
	v_add_u32_e32 v156, s62, v192
	ds_read_b128 v[104:107], v116
	ds_read_b128 v[108:111], v116 offset:1024
	ds_read_b128 v[112:115], v116 offset:2048
	ds_read_b128 v[116:119], v116 offset:3072
	ds_read_b128 v[144:147], v156
	ds_read_b128 v[148:151], v156 offset:1024
	ds_read_b128 v[152:155], v156 offset:2048
	ds_read_b128 v[156:159], v156 offset:3072
	s_add_u32 s2, s24, s78
	s_addc_u32 s3, s25, 0
	s_mov_b32 m0, s35
	v_lshl_add_u64 v[236:237], s[2:3], 0, v[168:169]
	ds_read_b128 v[160:163], v194 offset:32768
	ds_read_b128 v[164:167], v194 offset:33792
	ds_read_b128 v[196:199], v194 offset:34816
	ds_read_b128 v[200:203], v194 offset:35840
	ds_read_b128 v[210:213], v194 offset:36864
	ds_read_b128 v[214:217], v194 offset:37888
	ds_read_b128 v[218:221], v194 offset:38912
	ds_read_b128 v[222:225], v194 offset:39936
	global_load_lds_dwordx4 v[236:237], off
	v_lshl_add_u64 v[236:237], s[2:3], 0, v[170:171]
	s_mov_b32 m0, s36
	s_nop 0
	global_load_lds_dwordx4 v[236:237], off
	s_waitcnt vmcnt(8)
	s_waitcnt lgkmcnt(0)
	s_barrier
	s_setprio 1
	s_waitcnt lgkmcnt(0)
	v_mfma_f32_16x16x32_bf16 v[140:143], v[104:107], v[160:163], v[140:143]
	v_mfma_f32_16x16x32_bf16 v[140:143], v[108:111], v[164:167], v[140:143]
	v_mfma_f32_16x16x32_bf16 v[136:139], v[112:115], v[160:163], v[136:139]
	v_mfma_f32_16x16x32_bf16 v[136:139], v[116:119], v[164:167], v[136:139]
	v_mfma_f32_16x16x32_bf16 v[132:135], v[144:147], v[160:163], v[132:135]
	v_mfma_f32_16x16x32_bf16 v[132:135], v[148:151], v[164:167], v[132:135]
	v_mfma_f32_16x16x32_bf16 v[128:131], v[152:155], v[160:163], v[128:131]
	v_mfma_f32_16x16x32_bf16 v[128:131], v[156:159], v[164:167], v[128:131]
	v_mfma_f32_16x16x32_bf16 v[124:127], v[104:107], v[196:199], v[124:127]
	v_mfma_f32_16x16x32_bf16 v[124:127], v[108:111], v[200:203], v[124:127]
	v_mfma_f32_16x16x32_bf16 v[120:123], v[112:115], v[196:199], v[120:123]
	v_mfma_f32_16x16x32_bf16 v[120:123], v[116:119], v[200:203], v[120:123]
	v_mfma_f32_16x16x32_bf16 v[100:103], v[144:147], v[196:199], v[100:103]
	v_mfma_f32_16x16x32_bf16 v[100:103], v[148:151], v[200:203], v[100:103]
	v_mfma_f32_16x16x32_bf16 v[96:99], v[152:155], v[196:199], v[96:99]
	v_mfma_f32_16x16x32_bf16 v[96:99], v[156:159], v[200:203], v[96:99]
	v_mfma_f32_16x16x32_bf16 v[92:95], v[104:107], v[210:213], v[92:95]
	v_mfma_f32_16x16x32_bf16 v[92:95], v[108:111], v[214:217], v[92:95]
	v_mfma_f32_16x16x32_bf16 v[88:91], v[112:115], v[210:213], v[88:91]
	v_mfma_f32_16x16x32_bf16 v[88:91], v[116:119], v[214:217], v[88:91]
	v_mfma_f32_16x16x32_bf16 v[84:87], v[144:147], v[210:213], v[84:87]
	v_mfma_f32_16x16x32_bf16 v[84:87], v[148:151], v[214:217], v[84:87]
	v_mfma_f32_16x16x32_bf16 v[72:75], v[152:155], v[210:213], v[72:75]
	v_mfma_f32_16x16x32_bf16 v[72:75], v[156:159], v[214:217], v[72:75]
	v_mfma_f32_16x16x32_bf16 v[80:83], v[104:107], v[218:221], v[80:83]
	v_mfma_f32_16x16x32_bf16 v[80:83], v[108:111], v[222:225], v[80:83]
	v_mfma_f32_16x16x32_bf16 v[76:79], v[112:115], v[218:221], v[76:79]
	v_mfma_f32_16x16x32_bf16 v[76:79], v[116:119], v[222:225], v[76:79]
	v_mfma_f32_16x16x32_bf16 v[68:71], v[144:147], v[218:221], v[68:71]
	v_mfma_f32_16x16x32_bf16 v[68:71], v[148:151], v[222:225], v[68:71]
	v_mfma_f32_16x16x32_bf16 v[64:67], v[152:155], v[218:221], v[64:67]
	v_mfma_f32_16x16x32_bf16 v[64:67], v[156:159], v[222:225], v[64:67]
	s_setprio 0
	s_barrier
	s_add_i32 s2, s61, s30
	v_lshl_add_u64 v[190:191], v[190:191], 0, s[82:83]
	s_mov_b32 m0, s2
	ds_read_b128 v[160:163], v194 offset:49152
	ds_read_b128 v[164:167], v194 offset:50176
	ds_read_b128 v[196:199], v194 offset:51200
	ds_read_b128 v[200:203], v194 offset:52224
	ds_read_b128 v[210:213], v194 offset:53248
	ds_read_b128 v[214:217], v194 offset:54272
	ds_read_b128 v[218:221], v194 offset:55296
	ds_read_b128 v[222:225], v194 offset:56320
	global_load_lds_dwordx4 v[190:191], off
	v_lshl_add_u64 v[190:191], v[226:227], 0, s[82:83]
	s_add_i32 m0, s2, 0x2000
	s_add_i32 s2, s62, s30
	global_load_lds_dwordx4 v[190:191], off
	v_lshl_add_u64 v[190:191], v[228:229], 0, s[82:83]
	s_mov_b32 m0, s2
	s_nop 0
	global_load_lds_dwordx4 v[190:191], off
	v_lshl_add_u64 v[190:191], v[230:231], 0, s[82:83]
	s_add_i32 m0, s2, 0x2000
	s_nop 0
	global_load_lds_dwordx4 v[190:191], off
	v_lshl_add_u64 v[190:191], v[232:233], 0, s[82:83]
	s_mov_b32 m0, s47
	s_nop 0
	global_load_lds_dwordx4 v[190:191], off
	v_lshl_add_u64 v[190:191], v[234:235], 0, s[82:83]
	s_mov_b32 m0, s50
	s_nop 0
	global_load_lds_dwordx4 v[190:191], off
	s_waitcnt vmcnt(8)
	s_waitcnt lgkmcnt(0)
	s_barrier
	s_setprio 1
	s_waitcnt lgkmcnt(0)
	v_mfma_f32_16x16x32_bf16 v[60:63], v[104:107], v[160:163], v[60:63]
	v_mfma_f32_16x16x32_bf16 v[60:63], v[108:111], v[164:167], v[60:63]
	v_mfma_f32_16x16x32_bf16 v[56:59], v[112:115], v[160:163], v[56:59]
	v_mfma_f32_16x16x32_bf16 v[56:59], v[116:119], v[164:167], v[56:59]
	v_mfma_f32_16x16x32_bf16 v[52:55], v[144:147], v[160:163], v[52:55]
	v_mfma_f32_16x16x32_bf16 v[52:55], v[148:151], v[164:167], v[52:55]
	v_mfma_f32_16x16x32_bf16 v[48:51], v[152:155], v[160:163], v[48:51]
	v_mfma_f32_16x16x32_bf16 v[48:51], v[156:159], v[164:167], v[48:51]
	v_mfma_f32_16x16x32_bf16 v[44:47], v[104:107], v[196:199], v[44:47]
	v_mfma_f32_16x16x32_bf16 v[44:47], v[108:111], v[200:203], v[44:47]
	v_mfma_f32_16x16x32_bf16 v[40:43], v[112:115], v[196:199], v[40:43]
	v_mfma_f32_16x16x32_bf16 v[40:43], v[116:119], v[200:203], v[40:43]
	v_mfma_f32_16x16x32_bf16 v[32:35], v[144:147], v[196:199], v[32:35]
	v_mfma_f32_16x16x32_bf16 v[32:35], v[148:151], v[200:203], v[32:35]
	v_mfma_f32_16x16x32_bf16 v[24:27], v[152:155], v[196:199], v[24:27]
	v_mfma_f32_16x16x32_bf16 v[24:27], v[156:159], v[200:203], v[24:27]
	v_mfma_f32_16x16x32_bf16 v[36:39], v[104:107], v[210:213], v[36:39]
	v_mfma_f32_16x16x32_bf16 v[36:39], v[108:111], v[214:217], v[36:39]
	v_mfma_f32_16x16x32_bf16 v[28:31], v[112:115], v[210:213], v[28:31]
	v_mfma_f32_16x16x32_bf16 v[28:31], v[116:119], v[214:217], v[28:31]
	v_mfma_f32_16x16x32_bf16 v[16:19], v[144:147], v[210:213], v[16:19]
	v_mfma_f32_16x16x32_bf16 v[16:19], v[148:151], v[214:217], v[16:19]
	v_mfma_f32_16x16x32_bf16 v[8:11], v[152:155], v[210:213], v[8:11]
	v_mfma_f32_16x16x32_bf16 v[8:11], v[156:159], v[214:217], v[8:11]
	v_mfma_f32_16x16x32_bf16 v[20:23], v[104:107], v[218:221], v[20:23]
	v_mfma_f32_16x16x32_bf16 v[20:23], v[108:111], v[222:225], v[20:23]
	v_mfma_f32_16x16x32_bf16 v[12:15], v[112:115], v[218:221], v[12:15]
	v_mfma_f32_16x16x32_bf16 v[12:15], v[116:119], v[222:225], v[12:15]
	v_mfma_f32_16x16x32_bf16 v[4:7], v[144:147], v[218:221], v[4:7]
	v_mfma_f32_16x16x32_bf16 v[4:7], v[148:151], v[222:225], v[4:7]
	v_mfma_f32_16x16x32_bf16 v[0:3], v[152:155], v[218:221], v[0:3]
	v_mfma_f32_16x16x32_bf16 v[0:3], v[156:159], v[222:225], v[0:3]
	s_setprio 0
	s_barrier
	s_add_u32 s57, s57, 0x100
	s_addc_u32 s59, s59, 0
	s_add_u32 s22, s22, 0x100
	s_addc_u32 s23, s23, 0
	s_cmp_ge_u32 s60, s46
	s_mov_b32 s24, s60
	s_cbranch_scc0 .LBB0_183

.LBB0_241:
	s_ashr_i32 s35, s34, 31
	s_lshl_b64 s[12:13], s[34:35], 19
	s_add_u32 s36, s40, s12
	s_addc_u32 s37, s41, s13
	s_and_b64 s[12:13], s[4:5], exec
	s_cselect_b32 s7, s37, s11
	s_cselect_b32 s35, s36, s10
	s_ashr_i32 s31, s30, 31
	s_lshl_b64 s[12:13], s[30:31], 19
	s_add_u32 s50, s42, s12
	s_addc_u32 s51, s43, s13
	s_and_b64 s[12:13], s[4:5], exec
	s_cselect_b32 s31, s51, s9
	s_cselect_b32 s89, s50, s8
	s_add_u32 vcc_lo, s8, 0x100
	s_addc_u32 vcc_hi, s9, 0
	s_add_u32 s8, s10, 0x40080
	v_mov_b32_e32 v0, 0
	s_addc_u32 s9, s11, 0
	s_mov_b32 s12, -2
	v_mov_b32_e32 v1, v0
	v_mov_b32_e32 v2, v0
	v_mov_b32_e32 v3, v0
	v_mov_b32_e32 v4, v0
	v_mov_b32_e32 v5, v0
	v_mov_b32_e32 v6, v0
	v_mov_b32_e32 v7, v0
	v_mov_b32_e32 v16, v0
	v_mov_b32_e32 v17, v0
	v_mov_b32_e32 v18, v0
	v_mov_b32_e32 v19, v0
	v_mov_b32_e32 v20, v0
	v_mov_b32_e32 v21, v0
	v_mov_b32_e32 v22, v0
	v_mov_b32_e32 v23, v0
	v_mov_b32_e32 v32, v0
	v_mov_b32_e32 v33, v0
	v_mov_b32_e32 v34, v0
	v_mov_b32_e32 v35, v0
	v_mov_b32_e32 v36, v0
	v_mov_b32_e32 v37, v0
	v_mov_b32_e32 v38, v0
	v_mov_b32_e32 v39, v0
	v_mov_b32_e32 v48, v0
	v_mov_b32_e32 v49, v0
	v_mov_b32_e32 v50, v0
	v_mov_b32_e32 v51, v0
	v_mov_b32_e32 v52, v0
	v_mov_b32_e32 v53, v0
	v_mov_b32_e32 v54, v0
	v_mov_b32_e32 v55, v0
	v_mov_b32_e32 v8, v0
	v_mov_b32_e32 v9, v0
	v_mov_b32_e32 v10, v0
	v_mov_b32_e32 v11, v0
	v_mov_b32_e32 v12, v0
	v_mov_b32_e32 v13, v0
	v_mov_b32_e32 v14, v0
	v_mov_b32_e32 v15, v0
	v_mov_b32_e32 v24, v0
	v_mov_b32_e32 v25, v0
	v_mov_b32_e32 v26, v0
	v_mov_b32_e32 v27, v0
	v_mov_b32_e32 v28, v0
	v_mov_b32_e32 v29, v0
	v_mov_b32_e32 v30, v0
	v_mov_b32_e32 v31, v0
	v_mov_b32_e32 v40, v0
	v_mov_b32_e32 v41, v0
	v_mov_b32_e32 v42, v0
	v_mov_b32_e32 v43, v0
	v_mov_b32_e32 v44, v0
	v_mov_b32_e32 v45, v0
	v_mov_b32_e32 v46, v0
	v_mov_b32_e32 v47, v0
	v_mov_b32_e32 v56, v0
	v_mov_b32_e32 v57, v0
	v_mov_b32_e32 v58, v0
	v_mov_b32_e32 v59, v0
	v_mov_b32_e32 v60, v0
	v_mov_b32_e32 v61, v0
	v_mov_b32_e32 v62, v0
	v_mov_b32_e32 v63, v0
	v_mov_b32_e32 v64, v0
	v_mov_b32_e32 v65, v0
	v_mov_b32_e32 v66, v0
	v_mov_b32_e32 v67, v0
	v_mov_b32_e32 v68, v0
	v_mov_b32_e32 v69, v0
	v_mov_b32_e32 v70, v0
	v_mov_b32_e32 v71, v0
	v_mov_b32_e32 v80, v0
	v_mov_b32_e32 v81, v0
	v_mov_b32_e32 v82, v0
	v_mov_b32_e32 v83, v0
	v_mov_b32_e32 v84, v0
	v_mov_b32_e32 v85, v0
	v_mov_b32_e32 v86, v0
	v_mov_b32_e32 v87, v0
	v_mov_b32_e32 v96, v0
	v_mov_b32_e32 v97, v0
	v_mov_b32_e32 v98, v0
	v_mov_b32_e32 v99, v0
	v_mov_b32_e32 v100, v0
	v_mov_b32_e32 v101, v0
	v_mov_b32_e32 v102, v0
	v_mov_b32_e32 v103, v0
	v_mov_b32_e32 v112, v0
	v_mov_b32_e32 v113, v0
	v_mov_b32_e32 v114, v0
	v_mov_b32_e32 v115, v0
	v_mov_b32_e32 v116, v0
	v_mov_b32_e32 v117, v0
	v_mov_b32_e32 v118, v0
	v_mov_b32_e32 v119, v0
	v_mov_b32_e32 v72, v0
	v_mov_b32_e32 v73, v0
	v_mov_b32_e32 v74, v0
	v_mov_b32_e32 v75, v0
	v_mov_b32_e32 v76, v0
	v_mov_b32_e32 v77, v0
	v_mov_b32_e32 v78, v0
	v_mov_b32_e32 v79, v0
	v_mov_b32_e32 v88, v0
	v_mov_b32_e32 v89, v0
	v_mov_b32_e32 v90, v0
	v_mov_b32_e32 v91, v0
	v_mov_b32_e32 v92, v0
	v_mov_b32_e32 v93, v0
	v_mov_b32_e32 v94, v0
	v_mov_b32_e32 v95, v0
	v_mov_b32_e32 v104, v0
	v_mov_b32_e32 v105, v0
	v_mov_b32_e32 v106, v0
	v_mov_b32_e32 v107, v0
	v_mov_b32_e32 v108, v0
	v_mov_b32_e32 v109, v0
	v_mov_b32_e32 v110, v0
	v_mov_b32_e32 v111, v0
	v_mov_b32_e32 v120, v0
	v_mov_b32_e32 v121, v0
	v_mov_b32_e32 v122, v0
	v_mov_b32_e32 v123, v0
	v_mov_b32_e32 v124, v0
	v_mov_b32_e32 v125, v0
	v_mov_b32_e32 v126, v0
	v_mov_b32_e32 v127, v0
	v_readlane_b32 s2, v246, 42
	s_cmp_eq_u32 s2, 0
	s_cbranch_scc1 .LBB0_242
	s_add_u32 s2, s8, 0xfffc0080
	s_addc_u32 s3, s9, -1
	s_add_i32 s13, 0, 0x10000
	s_cmp_eq_u32 s12, 12
	s_cselect_b32 s53, s7, s3
	s_cselect_b32 s52, s35, s2
	v_add_u32_e32 v156, s13, v164
	s_cselect_b32 s11, s31, vcc_hi
	s_cselect_b32 s10, s89, vcc_lo
	s_add_i32 s77, 0, 0x14000
	ds_read_b128 v[144:147], v156
	ds_read_b128 v[148:151], v156 offset:1024
	ds_read_b128 v[152:155], v156 offset:2048
	ds_read_b128 v[166:169], v156 offset:3072
	v_add_u32_e32 v156, s77, v164
	ds_read_b128 v[184:187], v156
	ds_read_b128 v[188:191], v156 offset:1024
	ds_read_b128 v[192:195], v156 offset:2048
	ds_read_b128 v[196:199], v156 offset:3072
	v_lshl_add_u64 v[156:157], s[8:9], 0, v[142:143]
	s_add_i32 m0, s19, 0xc000
	ds_read_b128 v[200:203], v165
	ds_read_b128 v[210:213], v165 offset:1024
	ds_read_b128 v[214:217], v165 offset:2048
	ds_read_b128 v[218:221], v165 offset:3072
	ds_read_b128 v[222:225], v165 offset:4096
	ds_read_b128 v[226:229], v165 offset:5120
	ds_read_b128 v[230:233], v165 offset:6144
	ds_read_b128 v[234:237], v165 offset:7168
	global_load_lds_dwordx4 v[156:157], off
	v_lshl_add_u64 v[156:157], s[8:9], 0, v[140:141]
	s_add_i32 m0, s19, 0xe000
	s_nop 0
	global_load_lds_dwordx4 v[156:157], off
	s_waitcnt vmcnt(24)
	s_waitcnt lgkmcnt(0)
	s_barrier
	s_setprio 1
	s_waitcnt lgkmcnt(0)
	v_mfma_f32_16x16x32_bf16 v[124:127], v[144:147], v[200:203], v[124:127]
	v_mfma_f32_16x16x32_bf16 v[124:127], v[148:151], v[210:213], v[124:127]
	v_mfma_f32_16x16x32_bf16 v[120:123], v[152:155], v[200:203], v[120:123]
	v_mfma_f32_16x16x32_bf16 v[120:123], v[166:169], v[210:213], v[120:123]
	v_mfma_f32_16x16x32_bf16 v[116:119], v[184:187], v[200:203], v[116:119]
	v_mfma_f32_16x16x32_bf16 v[116:119], v[188:191], v[210:213], v[116:119]
	v_mfma_f32_16x16x32_bf16 v[112:115], v[192:195], v[200:203], v[112:115]
	v_mfma_f32_16x16x32_bf16 v[112:115], v[196:199], v[210:213], v[112:115]
	v_mfma_f32_16x16x32_bf16 v[108:111], v[144:147], v[214:217], v[108:111]
	v_mfma_f32_16x16x32_bf16 v[108:111], v[148:151], v[218:221], v[108:111]
	v_mfma_f32_16x16x32_bf16 v[104:107], v[152:155], v[214:217], v[104:107]
	v_mfma_f32_16x16x32_bf16 v[104:107], v[166:169], v[218:221], v[104:107]
	v_mfma_f32_16x16x32_bf16 v[100:103], v[184:187], v[214:217], v[100:103]
	v_mfma_f32_16x16x32_bf16 v[100:103], v[188:191], v[218:221], v[100:103]
	v_mfma_f32_16x16x32_bf16 v[96:99], v[192:195], v[214:217], v[96:99]
	v_mfma_f32_16x16x32_bf16 v[96:99], v[196:199], v[218:221], v[96:99]
	v_mfma_f32_16x16x32_bf16 v[92:95], v[144:147], v[222:225], v[92:95]
	v_mfma_f32_16x16x32_bf16 v[92:95], v[148:151], v[226:229], v[92:95]
	v_mfma_f32_16x16x32_bf16 v[88:91], v[152:155], v[222:225], v[88:91]
	v_mfma_f32_16x16x32_bf16 v[88:91], v[166:169], v[226:229], v[88:91]
	v_mfma_f32_16x16x32_bf16 v[84:87], v[184:187], v[222:225], v[84:87]
	v_mfma_f32_16x16x32_bf16 v[84:87], v[188:191], v[226:229], v[84:87]
	v_mfma_f32_16x16x32_bf16 v[80:83], v[192:195], v[222:225], v[80:83]
	v_mfma_f32_16x16x32_bf16 v[80:83], v[196:199], v[226:229], v[80:83]
	v_mfma_f32_16x16x32_bf16 v[76:79], v[144:147], v[230:233], v[76:79]
	v_mfma_f32_16x16x32_bf16 v[76:79], v[148:151], v[234:237], v[76:79]
	v_mfma_f32_16x16x32_bf16 v[72:75], v[152:155], v[230:233], v[72:75]
	v_mfma_f32_16x16x32_bf16 v[72:75], v[166:169], v[234:237], v[72:75]
	v_mfma_f32_16x16x32_bf16 v[68:71], v[184:187], v[230:233], v[68:71]
	v_mfma_f32_16x16x32_bf16 v[68:71], v[188:191], v[234:237], v[68:71]
	v_mfma_f32_16x16x32_bf16 v[64:67], v[192:195], v[230:233], v[64:67]
	v_mfma_f32_16x16x32_bf16 v[64:67], v[196:199], v[234:237], v[64:67]
	s_setprio 0
	s_barrier
	s_add_i32 s2, s13, s56
	v_lshl_add_u64 v[156:157], s[10:11], 0, v[174:175]
	s_mov_b32 m0, s2
	ds_read_b128 v[200:203], v165 offset:16384
	ds_read_b128 v[210:213], v165 offset:17408
	ds_read_b128 v[214:217], v165 offset:18432
	ds_read_b128 v[218:221], v165 offset:19456
	ds_read_b128 v[222:225], v165 offset:20480
	ds_read_b128 v[226:229], v165 offset:21504
	ds_read_b128 v[230:233], v165 offset:22528
	ds_read_b128 v[234:237], v165 offset:23552
	global_load_lds_dwordx4 v[156:157], off
	s_add_i32 m0, s2, 0x2000
	s_add_u32 s2, s10, 0x40000
	v_lshl_add_u64 v[170:171], s[10:11], 0, v[132:133]
	s_addc_u32 s3, s11, 0
	s_add_i32 s13, s77, s56
	global_load_lds_dwordx4 v[170:171], off
	v_lshl_add_u64 v[238:239], s[2:3], 0, v[174:175]
	s_mov_b32 m0, s13
	v_lshl_add_u64 v[240:241], s[52:53], 0, v[130:131]
	global_load_lds_dwordx4 v[238:239], off
	v_lshl_add_u64 v[238:239], s[2:3], 0, v[132:133]
	s_add_i32 m0, s13, 0x2000
	s_nop 0
	global_load_lds_dwordx4 v[238:239], off
	v_lshl_add_u64 v[238:239], s[52:53], 0, v[128:129]
	s_mov_b32 m0, s19
	s_nop 0
	global_load_lds_dwordx4 v[238:239], off
	s_mov_b32 m0, s57
	s_nop 0
	global_load_lds_dwordx4 v[240:241], off
	s_waitcnt vmcnt(24)
	s_waitcnt lgkmcnt(0)
	s_barrier
	s_setprio 1
	s_waitcnt lgkmcnt(0)
	v_mfma_f32_16x16x32_bf16 v[60:63], v[144:147], v[200:203], v[60:63]
	v_mfma_f32_16x16x32_bf16 v[60:63], v[148:151], v[210:213], v[60:63]
	v_mfma_f32_16x16x32_bf16 v[56:59], v[152:155], v[200:203], v[56:59]
	v_mfma_f32_16x16x32_bf16 v[56:59], v[166:169], v[210:213], v[56:59]
	v_mfma_f32_16x16x32_bf16 v[52:55], v[184:187], v[200:203], v[52:55]
	v_mfma_f32_16x16x32_bf16 v[52:55], v[188:191], v[210:213], v[52:55]
	v_mfma_f32_16x16x32_bf16 v[48:51], v[192:195], v[200:203], v[48:51]
	v_mfma_f32_16x16x32_bf16 v[48:51], v[196:199], v[210:213], v[48:51]
	v_mfma_f32_16x16x32_bf16 v[44:47], v[144:147], v[214:217], v[44:47]
	v_mfma_f32_16x16x32_bf16 v[44:47], v[148:151], v[218:221], v[44:47]
	v_mfma_f32_16x16x32_bf16 v[40:43], v[152:155], v[214:217], v[40:43]
	v_mfma_f32_16x16x32_bf16 v[40:43], v[166:169], v[218:221], v[40:43]
	v_mfma_f32_16x16x32_bf16 v[36:39], v[184:187], v[214:217], v[36:39]
	v_mfma_f32_16x16x32_bf16 v[36:39], v[188:191], v[218:221], v[36:39]
	v_mfma_f32_16x16x32_bf16 v[32:35], v[192:195], v[214:217], v[32:35]
	v_mfma_f32_16x16x32_bf16 v[32:35], v[196:199], v[218:221], v[32:35]
	v_mfma_f32_16x16x32_bf16 v[28:31], v[144:147], v[222:225], v[28:31]
	v_mfma_f32_16x16x32_bf16 v[28:31], v[148:151], v[226:229], v[28:31]
	v_mfma_f32_16x16x32_bf16 v[24:27], v[152:155], v[222:225], v[24:27]
	v_mfma_f32_16x16x32_bf16 v[24:27], v[166:169], v[226:229], v[24:27]
	v_mfma_f32_16x16x32_bf16 v[20:23], v[184:187], v[222:225], v[20:23]
	v_mfma_f32_16x16x32_bf16 v[20:23], v[188:191], v[226:229], v[20:23]
	v_mfma_f32_16x16x32_bf16 v[16:19], v[192:195], v[222:225], v[16:19]
	v_mfma_f32_16x16x32_bf16 v[16:19], v[196:199], v[226:229], v[16:19]
	v_mfma_f32_16x16x32_bf16 v[12:15], v[144:147], v[230:233], v[12:15]
	v_mfma_f32_16x16x32_bf16 v[12:15], v[148:151], v[234:237], v[12:15]
	v_mfma_f32_16x16x32_bf16 v[8:11], v[152:155], v[230:233], v[8:11]
	v_mfma_f32_16x16x32_bf16 v[8:11], v[166:169], v[234:237], v[8:11]
	v_mfma_f32_16x16x32_bf16 v[4:7], v[184:187], v[230:233], v[4:7]
	v_mfma_f32_16x16x32_bf16 v[4:7], v[188:191], v[234:237], v[4:7]
	v_mfma_f32_16x16x32_bf16 v[0:3], v[192:195], v[230:233], v[0:3]
	v_mfma_f32_16x16x32_bf16 v[0:3], v[196:199], v[234:237], v[0:3]
	s_setprio 0
	s_barrier
	s_add_i32 s13, 0, 0x18000
	s_add_i32 s77, 0, 0x1c000
	v_add_u32_e32 v166, s13, v164
	v_add_u32_e32 v183, s77, v164
	ds_read_b128 v[144:147], v166
	ds_read_b128 v[148:151], v166 offset:1024
	ds_read_b128 v[152:155], v166 offset:2048
	ds_read_b128 v[166:169], v166 offset:3072
	ds_read_b128 v[184:187], v183
	ds_read_b128 v[188:191], v183 offset:1024
	ds_read_b128 v[192:195], v183 offset:2048
	ds_read_b128 v[196:199], v183 offset:3072
	s_add_u32 s2, s52, 0x40000
	s_addc_u32 s3, s53, 0
	s_mov_b32 m0, s60
	v_lshl_add_u64 v[242:243], s[2:3], 0, v[128:129]
	ds_read_b128 v[200:203], v165 offset:32768
	ds_read_b128 v[210:213], v165 offset:33792
	ds_read_b128 v[214:217], v165 offset:34816
	ds_read_b128 v[218:221], v165 offset:35840
	ds_read_b128 v[222:225], v165 offset:36864
	ds_read_b128 v[226:229], v165 offset:37888
	ds_read_b128 v[230:233], v165 offset:38912
	ds_read_b128 v[234:237], v165 offset:39936
	global_load_lds_dwordx4 v[242:243], off
	v_lshl_add_u64 v[242:243], s[2:3], 0, v[130:131]
	s_mov_b32 m0, s61
	s_nop 0
	global_load_lds_dwordx4 v[242:243], off
	s_waitcnt vmcnt(8)
	s_waitcnt lgkmcnt(0)
	s_barrier
	s_setprio 1
	s_waitcnt lgkmcnt(0)
	v_mfma_f32_16x16x32_bf16 v[124:127], v[144:147], v[200:203], v[124:127]
	v_mfma_f32_16x16x32_bf16 v[124:127], v[148:151], v[210:213], v[124:127]
	v_mfma_f32_16x16x32_bf16 v[120:123], v[152:155], v[200:203], v[120:123]
	v_mfma_f32_16x16x32_bf16 v[120:123], v[166:169], v[210:213], v[120:123]
	v_mfma_f32_16x16x32_bf16 v[116:119], v[184:187], v[200:203], v[116:119]
	v_mfma_f32_16x16x32_bf16 v[116:119], v[188:191], v[210:213], v[116:119]
	v_mfma_f32_16x16x32_bf16 v[112:115], v[192:195], v[200:203], v[112:115]
	v_mfma_f32_16x16x32_bf16 v[112:115], v[196:199], v[210:213], v[112:115]
	v_mfma_f32_16x16x32_bf16 v[108:111], v[144:147], v[214:217], v[108:111]
	v_mfma_f32_16x16x32_bf16 v[108:111], v[148:151], v[218:221], v[108:111]
	v_mfma_f32_16x16x32_bf16 v[104:107], v[152:155], v[214:217], v[104:107]
	v_mfma_f32_16x16x32_bf16 v[104:107], v[166:169], v[218:221], v[104:107]
	v_mfma_f32_16x16x32_bf16 v[100:103], v[184:187], v[214:217], v[100:103]
	v_mfma_f32_16x16x32_bf16 v[100:103], v[188:191], v[218:221], v[100:103]
	v_mfma_f32_16x16x32_bf16 v[96:99], v[192:195], v[214:217], v[96:99]
	v_mfma_f32_16x16x32_bf16 v[96:99], v[196:199], v[218:221], v[96:99]
	v_mfma_f32_16x16x32_bf16 v[92:95], v[144:147], v[222:225], v[92:95]
	v_mfma_f32_16x16x32_bf16 v[92:95], v[148:151], v[226:229], v[92:95]
	v_mfma_f32_16x16x32_bf16 v[88:91], v[152:155], v[222:225], v[88:91]
	v_mfma_f32_16x16x32_bf16 v[88:91], v[166:169], v[226:229], v[88:91]
	v_mfma_f32_16x16x32_bf16 v[84:87], v[184:187], v[222:225], v[84:87]
	v_mfma_f32_16x16x32_bf16 v[84:87], v[188:191], v[226:229], v[84:87]
	v_mfma_f32_16x16x32_bf16 v[80:83], v[192:195], v[222:225], v[80:83]
	v_mfma_f32_16x16x32_bf16 v[80:83], v[196:199], v[226:229], v[80:83]
	v_mfma_f32_16x16x32_bf16 v[76:79], v[144:147], v[230:233], v[76:79]
	v_mfma_f32_16x16x32_bf16 v[76:79], v[148:151], v[234:237], v[76:79]
	v_mfma_f32_16x16x32_bf16 v[72:75], v[152:155], v[230:233], v[72:75]
	v_mfma_f32_16x16x32_bf16 v[72:75], v[166:169], v[234:237], v[72:75]
	v_mfma_f32_16x16x32_bf16 v[68:71], v[184:187], v[230:233], v[68:71]
	v_mfma_f32_16x16x32_bf16 v[68:71], v[188:191], v[234:237], v[68:71]
	v_mfma_f32_16x16x32_bf16 v[64:67], v[192:195], v[230:233], v[64:67]
	v_mfma_f32_16x16x32_bf16 v[64:67], v[196:199], v[234:237], v[64:67]
	s_setprio 0
	s_barrier
	s_add_i32 s2, s13, s56
	v_lshl_add_u64 v[156:157], v[156:157], 0, s[82:83]
	s_mov_b32 m0, s2
	ds_read_b128 v[200:203], v165 offset:49152
	ds_read_b128 v[210:213], v165 offset:50176
	ds_read_b128 v[214:217], v165 offset:51200
	ds_read_b128 v[218:221], v165 offset:52224
	ds_read_b128 v[222:225], v165 offset:53248
	ds_read_b128 v[226:229], v165 offset:54272
	ds_read_b128 v[230:233], v165 offset:55296
	ds_read_b128 v[234:237], v165 offset:56320
	global_load_lds_dwordx4 v[156:157], off
	s_add_i32 m0, s2, 0x2000
	s_add_u32 s2, s10, 0x40080
	v_lshl_add_u64 v[156:157], v[170:171], 0, s[82:83]
	s_addc_u32 s3, s11, 0
	s_add_i32 s10, s77, s56
	global_load_lds_dwordx4 v[156:157], off
	v_lshl_add_u64 v[156:157], s[2:3], 0, v[174:175]
	s_mov_b32 m0, s10
	s_nop 0
	global_load_lds_dwordx4 v[156:157], off
	v_lshl_add_u64 v[156:157], s[2:3], 0, v[132:133]
	s_add_i32 m0, s10, 0x2000
	s_nop 0
	global_load_lds_dwordx4 v[156:157], off
	v_lshl_add_u64 v[156:157], v[238:239], 0, s[82:83]
	s_mov_b32 m0, s39
	s_nop 0
	global_load_lds_dwordx4 v[156:157], off
	v_lshl_add_u64 v[156:157], v[240:241], 0, s[82:83]
	s_mov_b32 m0, s46
	s_nop 0
	global_load_lds_dwordx4 v[156:157], off
	s_waitcnt vmcnt(8)
	s_waitcnt lgkmcnt(0)
	s_barrier
	s_setprio 1
	s_waitcnt lgkmcnt(0)
	v_mfma_f32_16x16x32_bf16 v[60:63], v[144:147], v[200:203], v[60:63]
	v_mfma_f32_16x16x32_bf16 v[60:63], v[148:151], v[210:213], v[60:63]
	v_mfma_f32_16x16x32_bf16 v[56:59], v[152:155], v[200:203], v[56:59]
	v_mfma_f32_16x16x32_bf16 v[56:59], v[166:169], v[210:213], v[56:59]
	v_mfma_f32_16x16x32_bf16 v[52:55], v[184:187], v[200:203], v[52:55]
	v_mfma_f32_16x16x32_bf16 v[52:55], v[188:191], v[210:213], v[52:55]
	v_mfma_f32_16x16x32_bf16 v[48:51], v[192:195], v[200:203], v[48:51]
	v_mfma_f32_16x16x32_bf16 v[48:51], v[196:199], v[210:213], v[48:51]
	v_mfma_f32_16x16x32_bf16 v[44:47], v[144:147], v[214:217], v[44:47]
	v_mfma_f32_16x16x32_bf16 v[44:47], v[148:151], v[218:221], v[44:47]
	v_mfma_f32_16x16x32_bf16 v[40:43], v[152:155], v[214:217], v[40:43]
	v_mfma_f32_16x16x32_bf16 v[40:43], v[166:169], v[218:221], v[40:43]
	v_mfma_f32_16x16x32_bf16 v[36:39], v[184:187], v[214:217], v[36:39]
	v_mfma_f32_16x16x32_bf16 v[36:39], v[188:191], v[218:221], v[36:39]
	v_mfma_f32_16x16x32_bf16 v[32:35], v[192:195], v[214:217], v[32:35]
	v_mfma_f32_16x16x32_bf16 v[32:35], v[196:199], v[218:221], v[32:35]
	v_mfma_f32_16x16x32_bf16 v[28:31], v[144:147], v[222:225], v[28:31]
	v_mfma_f32_16x16x32_bf16 v[28:31], v[148:151], v[226:229], v[28:31]
	v_mfma_f32_16x16x32_bf16 v[24:27], v[152:155], v[222:225], v[24:27]
	v_mfma_f32_16x16x32_bf16 v[24:27], v[166:169], v[226:229], v[24:27]
	v_mfma_f32_16x16x32_bf16 v[20:23], v[184:187], v[222:225], v[20:23]
	v_mfma_f32_16x16x32_bf16 v[20:23], v[188:191], v[226:229], v[20:23]
	v_mfma_f32_16x16x32_bf16 v[16:19], v[192:195], v[222:225], v[16:19]
	v_mfma_f32_16x16x32_bf16 v[16:19], v[196:199], v[226:229], v[16:19]
	v_mfma_f32_16x16x32_bf16 v[12:15], v[144:147], v[230:233], v[12:15]
	v_mfma_f32_16x16x32_bf16 v[12:15], v[148:151], v[234:237], v[12:15]
	v_mfma_f32_16x16x32_bf16 v[8:11], v[152:155], v[230:233], v[8:11]
	v_mfma_f32_16x16x32_bf16 v[8:11], v[166:169], v[234:237], v[8:11]
	v_mfma_f32_16x16x32_bf16 v[4:7], v[184:187], v[230:233], v[4:7]
	v_mfma_f32_16x16x32_bf16 v[4:7], v[188:191], v[234:237], v[4:7]
	v_mfma_f32_16x16x32_bf16 v[0:3], v[192:195], v[230:233], v[0:3]
	v_mfma_f32_16x16x32_bf16 v[0:3], v[196:199], v[234:237], v[0:3]
	s_setprio 0
	s_barrier
	s_add_i32 s12, s12, 2
	s_add_u32 vcc_lo, vcc_lo, 0x100
	s_addc_u32 vcc_hi, vcc_hi, 0
	s_add_u32 s8, s8, 0x100
	s_addc_u32 s9, s9, 0
	s_cmp_gt_u32 s12, 13
	s_cbranch_scc1 .Lexit_242
.LBB0_242:
	s_add_u32 s2, s8, 0xfffc0080
	s_addc_u32 s3, s9, -1
	s_add_i32 s13, 0, 0x10000
	s_cmp_eq_u32 s12, 12
	s_cselect_b32 s53, s7, s3
	s_cselect_b32 s52, s35, s2
	v_add_u32_e32 v156, s13, v164
	s_cselect_b32 s11, s31, vcc_hi
	s_cselect_b32 s10, s89, vcc_lo
	s_add_i32 s77, 0, 0x14000
	ds_read_b128 v[144:147], v156
	ds_read_b128 v[148:151], v156 offset:1024
	ds_read_b128 v[152:155], v156 offset:2048
	ds_read_b128 v[166:169], v156 offset:3072
	v_add_u32_e32 v156, s77, v164
	ds_read_b128 v[184:187], v156
	ds_read_b128 v[188:191], v156 offset:1024
	ds_read_b128 v[192:195], v156 offset:2048
	ds_read_b128 v[196:199], v156 offset:3072
	v_lshl_add_u64 v[156:157], s[8:9], 0, v[142:143]
	s_add_i32 m0, s19, 0xc000
	ds_read_b128 v[200:203], v165
	ds_read_b128 v[210:213], v165 offset:1024
	ds_read_b128 v[214:217], v165 offset:2048
	ds_read_b128 v[218:221], v165 offset:3072
	ds_read_b128 v[222:225], v165 offset:4096
	ds_read_b128 v[226:229], v165 offset:5120
	ds_read_b128 v[230:233], v165 offset:6144
	ds_read_b128 v[234:237], v165 offset:7168
	global_load_lds_dwordx4 v[156:157], off
	v_lshl_add_u64 v[156:157], s[8:9], 0, v[140:141]
	s_add_i32 m0, s19, 0xe000
	s_nop 0
	global_load_lds_dwordx4 v[156:157], off
	s_waitcnt vmcnt(8)
	s_waitcnt lgkmcnt(0)
	s_barrier
	s_setprio 1
	s_waitcnt lgkmcnt(0)
	v_mfma_f32_16x16x32_bf16 v[124:127], v[144:147], v[200:203], v[124:127]
	v_mfma_f32_16x16x32_bf16 v[124:127], v[148:151], v[210:213], v[124:127]
	v_mfma_f32_16x16x32_bf16 v[120:123], v[152:155], v[200:203], v[120:123]
	v_mfma_f32_16x16x32_bf16 v[120:123], v[166:169], v[210:213], v[120:123]
	v_mfma_f32_16x16x32_bf16 v[116:119], v[184:187], v[200:203], v[116:119]
	v_mfma_f32_16x16x32_bf16 v[116:119], v[188:191], v[210:213], v[116:119]
	v_mfma_f32_16x16x32_bf16 v[112:115], v[192:195], v[200:203], v[112:115]
	v_mfma_f32_16x16x32_bf16 v[112:115], v[196:199], v[210:213], v[112:115]
	v_mfma_f32_16x16x32_bf16 v[108:111], v[144:147], v[214:217], v[108:111]
	v_mfma_f32_16x16x32_bf16 v[108:111], v[148:151], v[218:221], v[108:111]
	v_mfma_f32_16x16x32_bf16 v[104:107], v[152:155], v[214:217], v[104:107]
	v_mfma_f32_16x16x32_bf16 v[104:107], v[166:169], v[218:221], v[104:107]
	v_mfma_f32_16x16x32_bf16 v[100:103], v[184:187], v[214:217], v[100:103]
	v_mfma_f32_16x16x32_bf16 v[100:103], v[188:191], v[218:221], v[100:103]
	v_mfma_f32_16x16x32_bf16 v[96:99], v[192:195], v[214:217], v[96:99]
	v_mfma_f32_16x16x32_bf16 v[96:99], v[196:199], v[218:221], v[96:99]
	v_mfma_f32_16x16x32_bf16 v[92:95], v[144:147], v[222:225], v[92:95]
	v_mfma_f32_16x16x32_bf16 v[92:95], v[148:151], v[226:229], v[92:95]
	v_mfma_f32_16x16x32_bf16 v[88:91], v[152:155], v[222:225], v[88:91]
	v_mfma_f32_16x16x32_bf16 v[88:91], v[166:169], v[226:229], v[88:91]
	v_mfma_f32_16x16x32_bf16 v[84:87], v[184:187], v[222:225], v[84:87]
	v_mfma_f32_16x16x32_bf16 v[84:87], v[188:191], v[226:229], v[84:87]
	v_mfma_f32_16x16x32_bf16 v[80:83], v[192:195], v[222:225], v[80:83]
	v_mfma_f32_16x16x32_bf16 v[80:83], v[196:199], v[226:229], v[80:83]
	v_mfma_f32_16x16x32_bf16 v[76:79], v[144:147], v[230:233], v[76:79]
	v_mfma_f32_16x16x32_bf16 v[76:79], v[148:151], v[234:237], v[76:79]
	v_mfma_f32_16x16x32_bf16 v[72:75], v[152:155], v[230:233], v[72:75]
	v_mfma_f32_16x16x32_bf16 v[72:75], v[166:169], v[234:237], v[72:75]
	v_mfma_f32_16x16x32_bf16 v[68:71], v[184:187], v[230:233], v[68:71]
	v_mfma_f32_16x16x32_bf16 v[68:71], v[188:191], v[234:237], v[68:71]
	v_mfma_f32_16x16x32_bf16 v[64:67], v[192:195], v[230:233], v[64:67]
	v_mfma_f32_16x16x32_bf16 v[64:67], v[196:199], v[234:237], v[64:67]
	s_setprio 0
	s_barrier
	s_add_i32 s2, s13, s56
	v_lshl_add_u64 v[156:157], s[10:11], 0, v[174:175]
	s_mov_b32 m0, s2
	ds_read_b128 v[200:203], v165 offset:16384
	ds_read_b128 v[210:213], v165 offset:17408
	ds_read_b128 v[214:217], v165 offset:18432
	ds_read_b128 v[218:221], v165 offset:19456
	ds_read_b128 v[222:225], v165 offset:20480
	ds_read_b128 v[226:229], v165 offset:21504
	ds_read_b128 v[230:233], v165 offset:22528
	ds_read_b128 v[234:237], v165 offset:23552
	global_load_lds_dwordx4 v[156:157], off
	s_add_i32 m0, s2, 0x2000
	s_add_u32 s2, s10, 0x40000
	v_lshl_add_u64 v[170:171], s[10:11], 0, v[132:133]
	s_addc_u32 s3, s11, 0
	s_add_i32 s13, s77, s56
	global_load_lds_dwordx4 v[170:171], off
	v_lshl_add_u64 v[238:239], s[2:3], 0, v[174:175]
	s_mov_b32 m0, s13
	v_lshl_add_u64 v[240:241], s[52:53], 0, v[130:131]
	global_load_lds_dwordx4 v[238:239], off
	v_lshl_add_u64 v[238:239], s[2:3], 0, v[132:133]
	s_add_i32 m0, s13, 0x2000
	s_nop 0
	global_load_lds_dwordx4 v[238:239], off
	v_lshl_add_u64 v[238:239], s[52:53], 0, v[128:129]
	s_mov_b32 m0, s19
	s_nop 0
	global_load_lds_dwordx4 v[238:239], off
	s_mov_b32 m0, s57
	s_nop 0
	global_load_lds_dwordx4 v[240:241], off
	s_waitcnt vmcnt(8)
	s_waitcnt lgkmcnt(0)
	s_barrier
	s_setprio 1
	s_waitcnt lgkmcnt(0)
	v_mfma_f32_16x16x32_bf16 v[60:63], v[144:147], v[200:203], v[60:63]
	v_mfma_f32_16x16x32_bf16 v[60:63], v[148:151], v[210:213], v[60:63]
	v_mfma_f32_16x16x32_bf16 v[56:59], v[152:155], v[200:203], v[56:59]
	v_mfma_f32_16x16x32_bf16 v[56:59], v[166:169], v[210:213], v[56:59]
	v_mfma_f32_16x16x32_bf16 v[52:55], v[184:187], v[200:203], v[52:55]
	v_mfma_f32_16x16x32_bf16 v[52:55], v[188:191], v[210:213], v[52:55]
	v_mfma_f32_16x16x32_bf16 v[48:51], v[192:195], v[200:203], v[48:51]
	v_mfma_f32_16x16x32_bf16 v[48:51], v[196:199], v[210:213], v[48:51]
	v_mfma_f32_16x16x32_bf16 v[44:47], v[144:147], v[214:217], v[44:47]
	v_mfma_f32_16x16x32_bf16 v[44:47], v[148:151], v[218:221], v[44:47]
	v_mfma_f32_16x16x32_bf16 v[40:43], v[152:155], v[214:217], v[40:43]
	v_mfma_f32_16x16x32_bf16 v[40:43], v[166:169], v[218:221], v[40:43]
	v_mfma_f32_16x16x32_bf16 v[36:39], v[184:187], v[214:217], v[36:39]
	v_mfma_f32_16x16x32_bf16 v[36:39], v[188:191], v[218:221], v[36:39]
	v_mfma_f32_16x16x32_bf16 v[32:35], v[192:195], v[214:217], v[32:35]
	v_mfma_f32_16x16x32_bf16 v[32:35], v[196:199], v[218:221], v[32:35]
	v_mfma_f32_16x16x32_bf16 v[28:31], v[144:147], v[222:225], v[28:31]
	v_mfma_f32_16x16x32_bf16 v[28:31], v[148:151], v[226:229], v[28:31]
	v_mfma_f32_16x16x32_bf16 v[24:27], v[152:155], v[222:225], v[24:27]
	v_mfma_f32_16x16x32_bf16 v[24:27], v[166:169], v[226:229], v[24:27]
	v_mfma_f32_16x16x32_bf16 v[20:23], v[184:187], v[222:225], v[20:23]
	v_mfma_f32_16x16x32_bf16 v[20:23], v[188:191], v[226:229], v[20:23]
	v_mfma_f32_16x16x32_bf16 v[16:19], v[192:195], v[222:225], v[16:19]
	v_mfma_f32_16x16x32_bf16 v[16:19], v[196:199], v[226:229], v[16:19]
	v_mfma_f32_16x16x32_bf16 v[12:15], v[144:147], v[230:233], v[12:15]
	v_mfma_f32_16x16x32_bf16 v[12:15], v[148:151], v[234:237], v[12:15]
	v_mfma_f32_16x16x32_bf16 v[8:11], v[152:155], v[230:233], v[8:11]
	v_mfma_f32_16x16x32_bf16 v[8:11], v[166:169], v[234:237], v[8:11]
	v_mfma_f32_16x16x32_bf16 v[4:7], v[184:187], v[230:233], v[4:7]
	v_mfma_f32_16x16x32_bf16 v[4:7], v[188:191], v[234:237], v[4:7]
	v_mfma_f32_16x16x32_bf16 v[0:3], v[192:195], v[230:233], v[0:3]
	v_mfma_f32_16x16x32_bf16 v[0:3], v[196:199], v[234:237], v[0:3]
	s_setprio 0
	s_barrier
	s_add_i32 s13, 0, 0x18000
	s_add_i32 s77, 0, 0x1c000
	v_add_u32_e32 v166, s13, v164
	v_add_u32_e32 v183, s77, v164
	ds_read_b128 v[144:147], v166
	ds_read_b128 v[148:151], v166 offset:1024
	ds_read_b128 v[152:155], v166 offset:2048
	ds_read_b128 v[166:169], v166 offset:3072
	ds_read_b128 v[184:187], v183
	ds_read_b128 v[188:191], v183 offset:1024
	ds_read_b128 v[192:195], v183 offset:2048
	ds_read_b128 v[196:199], v183 offset:3072
	s_add_u32 s2, s52, 0x40000
	s_addc_u32 s3, s53, 0
	s_mov_b32 m0, s60
	v_lshl_add_u64 v[242:243], s[2:3], 0, v[128:129]
	ds_read_b128 v[200:203], v165 offset:32768
	ds_read_b128 v[210:213], v165 offset:33792
	ds_read_b128 v[214:217], v165 offset:34816
	ds_read_b128 v[218:221], v165 offset:35840
	ds_read_b128 v[222:225], v165 offset:36864
	ds_read_b128 v[226:229], v165 offset:37888
	ds_read_b128 v[230:233], v165 offset:38912
	ds_read_b128 v[234:237], v165 offset:39936
	global_load_lds_dwordx4 v[242:243], off
	v_lshl_add_u64 v[242:243], s[2:3], 0, v[130:131]
	s_mov_b32 m0, s61
	s_nop 0
	global_load_lds_dwordx4 v[242:243], off
	s_waitcnt vmcnt(8)
	s_waitcnt lgkmcnt(0)
	s_barrier
	s_setprio 1
	s_waitcnt lgkmcnt(0)
	v_mfma_f32_16x16x32_bf16 v[124:127], v[144:147], v[200:203], v[124:127]
	v_mfma_f32_16x16x32_bf16 v[124:127], v[148:151], v[210:213], v[124:127]
	v_mfma_f32_16x16x32_bf16 v[120:123], v[152:155], v[200:203], v[120:123]
	v_mfma_f32_16x16x32_bf16 v[120:123], v[166:169], v[210:213], v[120:123]
	v_mfma_f32_16x16x32_bf16 v[116:119], v[184:187], v[200:203], v[116:119]
	v_mfma_f32_16x16x32_bf16 v[116:119], v[188:191], v[210:213], v[116:119]
	v_mfma_f32_16x16x32_bf16 v[112:115], v[192:195], v[200:203], v[112:115]
	v_mfma_f32_16x16x32_bf16 v[112:115], v[196:199], v[210:213], v[112:115]
	v_mfma_f32_16x16x32_bf16 v[108:111], v[144:147], v[214:217], v[108:111]
	v_mfma_f32_16x16x32_bf16 v[108:111], v[148:151], v[218:221], v[108:111]
	v_mfma_f32_16x16x32_bf16 v[104:107], v[152:155], v[214:217], v[104:107]
	v_mfma_f32_16x16x32_bf16 v[104:107], v[166:169], v[218:221], v[104:107]
	v_mfma_f32_16x16x32_bf16 v[100:103], v[184:187], v[214:217], v[100:103]
	v_mfma_f32_16x16x32_bf16 v[100:103], v[188:191], v[218:221], v[100:103]
	v_mfma_f32_16x16x32_bf16 v[96:99], v[192:195], v[214:217], v[96:99]
	v_mfma_f32_16x16x32_bf16 v[96:99], v[196:199], v[218:221], v[96:99]
	v_mfma_f32_16x16x32_bf16 v[92:95], v[144:147], v[222:225], v[92:95]
	v_mfma_f32_16x16x32_bf16 v[92:95], v[148:151], v[226:229], v[92:95]
	v_mfma_f32_16x16x32_bf16 v[88:91], v[152:155], v[222:225], v[88:91]
	v_mfma_f32_16x16x32_bf16 v[88:91], v[166:169], v[226:229], v[88:91]
	v_mfma_f32_16x16x32_bf16 v[84:87], v[184:187], v[222:225], v[84:87]
	v_mfma_f32_16x16x32_bf16 v[84:87], v[188:191], v[226:229], v[84:87]
	v_mfma_f32_16x16x32_bf16 v[80:83], v[192:195], v[222:225], v[80:83]
	v_mfma_f32_16x16x32_bf16 v[80:83], v[196:199], v[226:229], v[80:83]
	v_mfma_f32_16x16x32_bf16 v[76:79], v[144:147], v[230:233], v[76:79]
	v_mfma_f32_16x16x32_bf16 v[76:79], v[148:151], v[234:237], v[76:79]
	v_mfma_f32_16x16x32_bf16 v[72:75], v[152:155], v[230:233], v[72:75]
	v_mfma_f32_16x16x32_bf16 v[72:75], v[166:169], v[234:237], v[72:75]
	v_mfma_f32_16x16x32_bf16 v[68:71], v[184:187], v[230:233], v[68:71]
	v_mfma_f32_16x16x32_bf16 v[68:71], v[188:191], v[234:237], v[68:71]
	v_mfma_f32_16x16x32_bf16 v[64:67], v[192:195], v[230:233], v[64:67]
	v_mfma_f32_16x16x32_bf16 v[64:67], v[196:199], v[234:237], v[64:67]
	s_setprio 0
	s_barrier
	s_add_i32 s2, s13, s56
	v_lshl_add_u64 v[156:157], v[156:157], 0, s[82:83]
	s_mov_b32 m0, s2
	ds_read_b128 v[200:203], v165 offset:49152
	ds_read_b128 v[210:213], v165 offset:50176
	ds_read_b128 v[214:217], v165 offset:51200
	ds_read_b128 v[218:221], v165 offset:52224
	ds_read_b128 v[222:225], v165 offset:53248
	ds_read_b128 v[226:229], v165 offset:54272
	ds_read_b128 v[230:233], v165 offset:55296
	ds_read_b128 v[234:237], v165 offset:56320
	global_load_lds_dwordx4 v[156:157], off
	s_add_i32 m0, s2, 0x2000
	s_add_u32 s2, s10, 0x40080
	v_lshl_add_u64 v[156:157], v[170:171], 0, s[82:83]
	s_addc_u32 s3, s11, 0
	s_add_i32 s10, s77, s56
	global_load_lds_dwordx4 v[156:157], off
	v_lshl_add_u64 v[156:157], s[2:3], 0, v[174:175]
	s_mov_b32 m0, s10
	s_nop 0
	global_load_lds_dwordx4 v[156:157], off
	v_lshl_add_u64 v[156:157], s[2:3], 0, v[132:133]
	s_add_i32 m0, s10, 0x2000
	s_nop 0
	global_load_lds_dwordx4 v[156:157], off
	v_lshl_add_u64 v[156:157], v[238:239], 0, s[82:83]
	s_mov_b32 m0, s39
	s_nop 0
	global_load_lds_dwordx4 v[156:157], off
	v_lshl_add_u64 v[156:157], v[240:241], 0, s[82:83]
	s_mov_b32 m0, s46
	s_nop 0
	global_load_lds_dwordx4 v[156:157], off
	s_waitcnt vmcnt(8)
	s_waitcnt lgkmcnt(0)
	s_barrier
	s_setprio 1
	s_waitcnt lgkmcnt(0)
	v_mfma_f32_16x16x32_bf16 v[60:63], v[144:147], v[200:203], v[60:63]
	v_mfma_f32_16x16x32_bf16 v[60:63], v[148:151], v[210:213], v[60:63]
	v_mfma_f32_16x16x32_bf16 v[56:59], v[152:155], v[200:203], v[56:59]
	v_mfma_f32_16x16x32_bf16 v[56:59], v[166:169], v[210:213], v[56:59]
	v_mfma_f32_16x16x32_bf16 v[52:55], v[184:187], v[200:203], v[52:55]
	v_mfma_f32_16x16x32_bf16 v[52:55], v[188:191], v[210:213], v[52:55]
	v_mfma_f32_16x16x32_bf16 v[48:51], v[192:195], v[200:203], v[48:51]
	v_mfma_f32_16x16x32_bf16 v[48:51], v[196:199], v[210:213], v[48:51]
	v_mfma_f32_16x16x32_bf16 v[44:47], v[144:147], v[214:217], v[44:47]
	v_mfma_f32_16x16x32_bf16 v[44:47], v[148:151], v[218:221], v[44:47]
	v_mfma_f32_16x16x32_bf16 v[40:43], v[152:155], v[214:217], v[40:43]
	v_mfma_f32_16x16x32_bf16 v[40:43], v[166:169], v[218:221], v[40:43]
	v_mfma_f32_16x16x32_bf16 v[36:39], v[184:187], v[214:217], v[36:39]
	v_mfma_f32_16x16x32_bf16 v[36:39], v[188:191], v[218:221], v[36:39]
	v_mfma_f32_16x16x32_bf16 v[32:35], v[192:195], v[214:217], v[32:35]
	v_mfma_f32_16x16x32_bf16 v[32:35], v[196:199], v[218:221], v[32:35]
	v_mfma_f32_16x16x32_bf16 v[28:31], v[144:147], v[222:225], v[28:31]
	v_mfma_f32_16x16x32_bf16 v[28:31], v[148:151], v[226:229], v[28:31]
	v_mfma_f32_16x16x32_bf16 v[24:27], v[152:155], v[222:225], v[24:27]
	v_mfma_f32_16x16x32_bf16 v[24:27], v[166:169], v[226:229], v[24:27]
	v_mfma_f32_16x16x32_bf16 v[20:23], v[184:187], v[222:225], v[20:23]
	v_mfma_f32_16x16x32_bf16 v[20:23], v[188:191], v[226:229], v[20:23]
	v_mfma_f32_16x16x32_bf16 v[16:19], v[192:195], v[222:225], v[16:19]
	v_mfma_f32_16x16x32_bf16 v[16:19], v[196:199], v[226:229], v[16:19]
	v_mfma_f32_16x16x32_bf16 v[12:15], v[144:147], v[230:233], v[12:15]
	v_mfma_f32_16x16x32_bf16 v[12:15], v[148:151], v[234:237], v[12:15]
	v_mfma_f32_16x16x32_bf16 v[8:11], v[152:155], v[230:233], v[8:11]
	v_mfma_f32_16x16x32_bf16 v[8:11], v[166:169], v[234:237], v[8:11]
	v_mfma_f32_16x16x32_bf16 v[4:7], v[184:187], v[230:233], v[4:7]
	v_mfma_f32_16x16x32_bf16 v[4:7], v[188:191], v[234:237], v[4:7]
	v_mfma_f32_16x16x32_bf16 v[0:3], v[192:195], v[230:233], v[0:3]
	v_mfma_f32_16x16x32_bf16 v[0:3], v[196:199], v[234:237], v[0:3]
	s_setprio 0
	s_barrier
	s_add_i32 s12, s12, 2
	s_add_u32 vcc_lo, vcc_lo, 0x100
	s_addc_u32 vcc_hi, vcc_hi, 0
	s_add_u32 s8, s8, 0x100
	s_addc_u32 s9, s9, 0
	s_cmp_gt_u32 s12, 13
	s_cbranch_scc0 .LBB0_242
